# scan3 rewritten with 16-byte operand loads (k remapped), scan2 segment step issues all LDS operand reads up front with counted lgkmcnt waits
# speedup vs baseline: 1.0198x; 1.0074x over previous
; __device__ __forceinline__ void phase_scan3(const Params& p, const Lt& lt, unsigned char* lds) {
;     const int tid = lt.tid, w = __builtin_amdgcn_readfirstlane(tid >> 6);
;     const float* SS = (const float*)(p.ws + WS_SS); const float* Z = (const float*)(p.ws + WS_Z); float* yraw = (float*)(p.ws + WS_YRAW);
;     const int G = gridDim.x;
; #pragma unroll 1
;     for (int it = w * G + lt.bid; it < NH * NSEG; it += 8 * G) {
;         int lane = tid & 63; asm volatile("" : "+v"(lane));
;         const int h = it / NSEG, g = it % NSEG, fi = lane & 15, fq = lane >> 4;
;         const float* zb = Z + (size_t)(g * SEGLEN + fi) * RW + h * 64 + fq;
;         const float* sb = SS + (size_t)(h * NSEG + g) * 4096 + (size_t)fi * 64 + fq;
;         float* yb = yraw + (size_t)(g * SEGLEN + 4 * fq) * RW + h * 64 + fi;
;         float bv[4][16];
; #pragma unroll
;         for (int ti = 0; ti < 4; ++ti)
; #pragma unroll
;             for (int ks = 0; ks < 16; ++ks) bv[ti][ks] = sb[(size_t)ti * 16 * 64 + 4 * ks];
; #pragma unroll 1
;         for (int tt = 0; tt < 4; ++tt) {
;             float av[16];
; #pragma unroll
;             for (int ks = 0; ks < 16; ++ks) av[ks] = zb[(size_t)tt * 16 * RW + 4 * ks];
.LBB0_137:
	v_and_b32_e32 v0, 15, v14
	v_lshrrev_b32_e32 v1, 4, v14
	s_lshl_b32 s4, s0, 14
	s_mov_b32 s5, 0
	s_add_u32 s4, s8, s4
	s_addc_u32 s5, s9, 0
	v_lshlrev_b32_e32 v158, 8, v0
	v_lshl_add_u32 v158, v1, 6, v158
	v_mov_b32_e32 v159, 0
	v_lshl_add_u64 v[148:149], s[4:5], 0, v[158:159]
	s_movk_i32 s4, 0x1000
	s_mov_b32 s5, 0
	v_lshl_add_u64 v[150:151], v[148:149], 0, s[4:5]
	v_lshl_add_u64 v[152:153], v[150:151], 0, s[4:5]
	v_lshl_add_u64 v[154:155], v[152:153], 0, s[4:5]
	s_lshr_b32 s1, s0, 7
	s_and_b32 s10, s0, 0x7f
	s_mul_i32 s10, s10, 0x30000
	s_lshl_b32 s1, s1, 8
	s_add_u32 s10, s10, s1
	s_add_u32 s4, s62, 0x32fa0000
	s_addc_u32 s5, s63, 0
	s_add_u32 s4, s4, s10
	s_addc_u32 s5, s5, 0
	v_mul_u32_u24_e32 v158, 0xc00, v0
	v_lshl_add_u32 v158, v1, 6, v158
	v_lshl_add_u64 v[156:157], s[4:5], 0, v[158:159]
	s_add_u32 s4, s62, 0x2a780000
	s_addc_u32 s5, s63, 0
	s_add_u32 s4, s4, s10
	s_addc_u32 s5, s5, 0
	v_mul_u32_u24_e32 v158, 0x3000, v1
	v_lshl_add_u32 v158, v0, 2, v158
	v_lshl_add_u64 v[4:5], s[4:5], 0, v[158:159]
	s_movk_i32 s4, 0x1800
	s_mov_b32 s5, 0
	v_lshl_add_u64 v[6:7], v[4:5], 0, s[4:5]
	s_mov_b32 s4, 0xc000
	s_mov_b32 s5, 0
	global_load_dwordx4 v[16:19], v[148:149], off offset:0
	global_load_dwordx4 v[20:23], v[148:149], off offset:16
	global_load_dwordx4 v[24:27], v[148:149], off offset:32
	global_load_dwordx4 v[28:31], v[148:149], off offset:48
	global_load_dwordx4 v[32:35], v[150:151], off offset:0
	global_load_dwordx4 v[36:39], v[150:151], off offset:16
	global_load_dwordx4 v[40:43], v[150:151], off offset:32
	global_load_dwordx4 v[44:47], v[150:151], off offset:48
	global_load_dwordx4 v[48:51], v[152:153], off offset:0
	global_load_dwordx4 v[52:55], v[152:153], off offset:16
	global_load_dwordx4 v[56:59], v[152:153], off offset:32
	global_load_dwordx4 v[60:63], v[152:153], off offset:48
	global_load_dwordx4 v[64:67], v[154:155], off offset:0
	global_load_dwordx4 v[68:71], v[154:155], off offset:16
	global_load_dwordx4 v[72:75], v[154:155], off offset:32
	global_load_dwordx4 v[76:79], v[154:155], off offset:48
	global_load_dwordx4 v[80:83], v[156:157], off offset:0
	global_load_dwordx4 v[84:87], v[156:157], off offset:16
	global_load_dwordx4 v[88:91], v[156:157], off offset:32
	global_load_dwordx4 v[92:95], v[156:157], off offset:48
	global_load_dword v112, v[4:5], off
	global_load_dword v116, v[4:5], off offset:64
	global_load_dword v120, v[4:5], off offset:128
	global_load_dword v124, v[4:5], off offset:192
	global_load_dword v113, v[4:5], off offset:3072
	global_load_dword v117, v[4:5], off offset:3136
	global_load_dword v121, v[4:5], off offset:3200
	global_load_dword v125, v[4:5], off offset:3264
	global_load_dword v114, v[6:7], off
	global_load_dword v118, v[6:7], off offset:64
	global_load_dword v122, v[6:7], off offset:128
	global_load_dword v126, v[6:7], off offset:192
	global_load_dword v115, v[6:7], off offset:3072
	global_load_dword v119, v[6:7], off offset:3136
	global_load_dword v123, v[6:7], off offset:3200
	global_load_dword v127, v[6:7], off offset:3264
	v_mov_b32_e32 v144, v4
	v_mov_b32_e32 v145, v5
	v_mov_b32_e32 v146, v6
	v_mov_b32_e32 v147, v7
	v_lshl_add_u64 v[156:157], v[156:157], 0, s[4:5]
	v_lshl_add_u64 v[4:5], v[4:5], 0, s[4:5]
	v_lshl_add_u64 v[6:7], v[6:7], 0, s[4:5]
	global_load_dwordx4 v[96:99], v[156:157], off offset:0
	global_load_dwordx4 v[100:103], v[156:157], off offset:16
	global_load_dwordx4 v[104:107], v[156:157], off offset:32
	global_load_dwordx4 v[108:111], v[156:157], off offset:48
	global_load_dword v128, v[4:5], off
	global_load_dword v132, v[4:5], off offset:64
	global_load_dword v136, v[4:5], off offset:128
	global_load_dword v140, v[4:5], off offset:192
	global_load_dword v129, v[4:5], off offset:3072
	global_load_dword v133, v[4:5], off offset:3136
	global_load_dword v137, v[4:5], off offset:3200
	global_load_dword v141, v[4:5], off offset:3264
	global_load_dword v130, v[6:7], off
	global_load_dword v134, v[6:7], off offset:64
	global_load_dword v138, v[6:7], off offset:128
	global_load_dword v142, v[6:7], off offset:192
	global_load_dword v131, v[6:7], off offset:3072
	global_load_dword v135, v[6:7], off offset:3136
	global_load_dword v139, v[6:7], off offset:3200
	global_load_dword v143, v[6:7], off offset:3264
	s_waitcnt vmcnt(20)
; __device__ __forceinline__ void phase_scan3(const Params& p, const Lt& lt, unsigned char* lds) {
;     ...
;         for (int tt = 0; tt < 4; ++tt) {
;             float av[16];
; #pragma unroll
;             for (int ks = 0; ks < 16; ++ks) av[ks] = zb[(size_t)tt * 16 * RW + 4 * ks];
;             f32x4 acc[4];
; #pragma unroll
;             for (int ti = 0; ti < 4; ++ti)
; #pragma unroll
;                 for (int r = 0; r < 4; ++r) acc[ti][r] = yb[(size_t)(tt * 16 + r) * RW + ti * 16];
; #pragma unroll
;             for (int ks = 0; ks < 16; ++ks)
; #pragma unroll
;                 for (int ti = 0; ti < 4; ++ti) acc[ti] = __builtin_amdgcn_mfma_f32_16x16x4f32(av[ks], bv[ti][ks], acc[ti], 0, 0, 0);
; #pragma unroll
;             for (int ti = 0; ti < 4; ++ti)
; #pragma unroll
;                 for (int r = 0; r < 4; ++r) yb[(size_t)(tt * 16 + r) * RW + ti * 16] = acc[ti][r];
;         }
	v_mfma_f32_16x16x4_f32 v[112:115], v80, v16, v[112:115]
	v_mfma_f32_16x16x4_f32 v[116:119], v80, v32, v[116:119]
	v_mfma_f32_16x16x4_f32 v[120:123], v80, v48, v[120:123]
	v_mfma_f32_16x16x4_f32 v[124:127], v80, v64, v[124:127]
	v_mfma_f32_16x16x4_f32 v[112:115], v81, v17, v[112:115]
	v_mfma_f32_16x16x4_f32 v[116:119], v81, v33, v[116:119]
	v_mfma_f32_16x16x4_f32 v[120:123], v81, v49, v[120:123]
	v_mfma_f32_16x16x4_f32 v[124:127], v81, v65, v[124:127]
	v_mfma_f32_16x16x4_f32 v[112:115], v82, v18, v[112:115]
	v_mfma_f32_16x16x4_f32 v[116:119], v82, v34, v[116:119]
	v_mfma_f32_16x16x4_f32 v[120:123], v82, v50, v[120:123]
	v_mfma_f32_16x16x4_f32 v[124:127], v82, v66, v[124:127]
	v_mfma_f32_16x16x4_f32 v[112:115], v83, v19, v[112:115]
	v_mfma_f32_16x16x4_f32 v[116:119], v83, v35, v[116:119]
	v_mfma_f32_16x16x4_f32 v[120:123], v83, v51, v[120:123]
	v_mfma_f32_16x16x4_f32 v[124:127], v83, v67, v[124:127]
	v_mfma_f32_16x16x4_f32 v[112:115], v84, v20, v[112:115]
	v_mfma_f32_16x16x4_f32 v[116:119], v84, v36, v[116:119]
	v_mfma_f32_16x16x4_f32 v[120:123], v84, v52, v[120:123]
	v_mfma_f32_16x16x4_f32 v[124:127], v84, v68, v[124:127]
	v_mfma_f32_16x16x4_f32 v[112:115], v85, v21, v[112:115]
	v_mfma_f32_16x16x4_f32 v[116:119], v85, v37, v[116:119]
	v_mfma_f32_16x16x4_f32 v[120:123], v85, v53, v[120:123]
	v_mfma_f32_16x16x4_f32 v[124:127], v85, v69, v[124:127]
	v_mfma_f32_16x16x4_f32 v[112:115], v86, v22, v[112:115]
	v_mfma_f32_16x16x4_f32 v[116:119], v86, v38, v[116:119]
	v_mfma_f32_16x16x4_f32 v[120:123], v86, v54, v[120:123]
	v_mfma_f32_16x16x4_f32 v[124:127], v86, v70, v[124:127]
	v_mfma_f32_16x16x4_f32 v[112:115], v87, v23, v[112:115]
	v_mfma_f32_16x16x4_f32 v[116:119], v87, v39, v[116:119]
	v_mfma_f32_16x16x4_f32 v[120:123], v87, v55, v[120:123]
	v_mfma_f32_16x16x4_f32 v[124:127], v87, v71, v[124:127]
	v_mfma_f32_16x16x4_f32 v[112:115], v88, v24, v[112:115]
	v_mfma_f32_16x16x4_f32 v[116:119], v88, v40, v[116:119]
	v_mfma_f32_16x16x4_f32 v[120:123], v88, v56, v[120:123]
	v_mfma_f32_16x16x4_f32 v[124:127], v88, v72, v[124:127]
	v_mfma_f32_16x16x4_f32 v[112:115], v89, v25, v[112:115]
	v_mfma_f32_16x16x4_f32 v[116:119], v89, v41, v[116:119]
	v_mfma_f32_16x16x4_f32 v[120:123], v89, v57, v[120:123]
	v_mfma_f32_16x16x4_f32 v[124:127], v89, v73, v[124:127]
	v_mfma_f32_16x16x4_f32 v[112:115], v90, v26, v[112:115]
	v_mfma_f32_16x16x4_f32 v[116:119], v90, v42, v[116:119]
	v_mfma_f32_16x16x4_f32 v[120:123], v90, v58, v[120:123]
	v_mfma_f32_16x16x4_f32 v[124:127], v90, v74, v[124:127]
	v_mfma_f32_16x16x4_f32 v[112:115], v91, v27, v[112:115]
	v_mfma_f32_16x16x4_f32 v[116:119], v91, v43, v[116:119]
	v_mfma_f32_16x16x4_f32 v[120:123], v91, v59, v[120:123]
	v_mfma_f32_16x16x4_f32 v[124:127], v91, v75, v[124:127]
	v_mfma_f32_16x16x4_f32 v[112:115], v92, v28, v[112:115]
	v_mfma_f32_16x16x4_f32 v[116:119], v92, v44, v[116:119]
	v_mfma_f32_16x16x4_f32 v[120:123], v92, v60, v[120:123]
	v_mfma_f32_16x16x4_f32 v[124:127], v92, v76, v[124:127]
	v_mfma_f32_16x16x4_f32 v[112:115], v93, v29, v[112:115]
	v_mfma_f32_16x16x4_f32 v[116:119], v93, v45, v[116:119]
	v_mfma_f32_16x16x4_f32 v[120:123], v93, v61, v[120:123]
	v_mfma_f32_16x16x4_f32 v[124:127], v93, v77, v[124:127]
	v_mfma_f32_16x16x4_f32 v[112:115], v94, v30, v[112:115]
	v_mfma_f32_16x16x4_f32 v[116:119], v94, v46, v[116:119]
	v_mfma_f32_16x16x4_f32 v[120:123], v94, v62, v[120:123]
	v_mfma_f32_16x16x4_f32 v[124:127], v94, v78, v[124:127]
	v_mfma_f32_16x16x4_f32 v[112:115], v95, v31, v[112:115]
	v_mfma_f32_16x16x4_f32 v[116:119], v95, v47, v[116:119]
	v_mfma_f32_16x16x4_f32 v[120:123], v95, v63, v[120:123]
	v_mfma_f32_16x16x4_f32 v[124:127], v95, v79, v[124:127]
	s_nop 9
	global_store_dword v[144:145], v112, off
	global_store_dword v[144:145], v116, off offset:64
	global_store_dword v[144:145], v120, off offset:128
	global_store_dword v[144:145], v124, off offset:192
	global_store_dword v[144:145], v113, off offset:3072
	global_store_dword v[144:145], v117, off offset:3136
	global_store_dword v[144:145], v121, off offset:3200
	global_store_dword v[144:145], v125, off offset:3264
	global_store_dword v[146:147], v114, off
	global_store_dword v[146:147], v118, off offset:64
	global_store_dword v[146:147], v122, off offset:128
	global_store_dword v[146:147], v126, off offset:192
	global_store_dword v[146:147], v115, off offset:3072
	global_store_dword v[146:147], v119, off offset:3136
	global_store_dword v[146:147], v123, off offset:3200
	global_store_dword v[146:147], v127, off offset:3264
	v_mov_b32_e32 v144, v4
	v_mov_b32_e32 v145, v5
	v_mov_b32_e32 v146, v6
	v_mov_b32_e32 v147, v7
	v_lshl_add_u64 v[156:157], v[156:157], 0, s[4:5]
	v_lshl_add_u64 v[4:5], v[4:5], 0, s[4:5]
	v_lshl_add_u64 v[6:7], v[6:7], 0, s[4:5]
	global_load_dwordx4 v[80:83], v[156:157], off offset:0
	global_load_dwordx4 v[84:87], v[156:157], off offset:16
	global_load_dwordx4 v[88:91], v[156:157], off offset:32
	global_load_dwordx4 v[92:95], v[156:157], off offset:48
	global_load_dword v112, v[4:5], off
	global_load_dword v116, v[4:5], off offset:64
	global_load_dword v120, v[4:5], off offset:128
	global_load_dword v124, v[4:5], off offset:192
	global_load_dword v113, v[4:5], off offset:3072
	global_load_dword v117, v[4:5], off offset:3136
	global_load_dword v121, v[4:5], off offset:3200
	global_load_dword v125, v[4:5], off offset:3264
	global_load_dword v114, v[6:7], off
	global_load_dword v118, v[6:7], off offset:64
	global_load_dword v122, v[6:7], off offset:128
	global_load_dword v126, v[6:7], off offset:192
	global_load_dword v115, v[6:7], off offset:3072
	global_load_dword v119, v[6:7], off offset:3136
	global_load_dword v123, v[6:7], off offset:3200
	global_load_dword v127, v[6:7], off offset:3264
	s_waitcnt vmcnt(36)
; __device__ __forceinline__ void phase_scan3(const Params& p, const Lt& lt, unsigned char* lds) {
;     ...
;         for (int tt = 0; tt < 4; ++tt) {
;             float av[16];
; #pragma unroll
;             for (int ks = 0; ks < 16; ++ks) av[ks] = zb[(size_t)tt * 16 * RW + 4 * ks];
;             f32x4 acc[4];
; #pragma unroll
;             for (int ti = 0; ti < 4; ++ti)
; #pragma unroll
;                 for (int r = 0; r < 4; ++r) acc[ti][r] = yb[(size_t)(tt * 16 + r) * RW + ti * 16];
; #pragma unroll
;             for (int ks = 0; ks < 16; ++ks)
; #pragma unroll
;                 for (int ti = 0; ti < 4; ++ti) acc[ti] = __builtin_amdgcn_mfma_f32_16x16x4f32(av[ks], bv[ti][ks], acc[ti], 0, 0, 0);
; #pragma unroll
;             for (int ti = 0; ti < 4; ++ti)
; #pragma unroll
;                 for (int r = 0; r < 4; ++r) yb[(size_t)(tt * 16 + r) * RW + ti * 16] = acc[ti][r];
;         }
	v_mfma_f32_16x16x4_f32 v[128:131], v96, v16, v[128:131]
	v_mfma_f32_16x16x4_f32 v[132:135], v96, v32, v[132:135]
	v_mfma_f32_16x16x4_f32 v[136:139], v96, v48, v[136:139]
	v_mfma_f32_16x16x4_f32 v[140:143], v96, v64, v[140:143]
	v_mfma_f32_16x16x4_f32 v[128:131], v97, v17, v[128:131]
	v_mfma_f32_16x16x4_f32 v[132:135], v97, v33, v[132:135]
	v_mfma_f32_16x16x4_f32 v[136:139], v97, v49, v[136:139]
	v_mfma_f32_16x16x4_f32 v[140:143], v97, v65, v[140:143]
	v_mfma_f32_16x16x4_f32 v[128:131], v98, v18, v[128:131]
	v_mfma_f32_16x16x4_f32 v[132:135], v98, v34, v[132:135]
	v_mfma_f32_16x16x4_f32 v[136:139], v98, v50, v[136:139]
	v_mfma_f32_16x16x4_f32 v[140:143], v98, v66, v[140:143]
	v_mfma_f32_16x16x4_f32 v[128:131], v99, v19, v[128:131]
	v_mfma_f32_16x16x4_f32 v[132:135], v99, v35, v[132:135]
	v_mfma_f32_16x16x4_f32 v[136:139], v99, v51, v[136:139]
	v_mfma_f32_16x16x4_f32 v[140:143], v99, v67, v[140:143]
	v_mfma_f32_16x16x4_f32 v[128:131], v100, v20, v[128:131]
	v_mfma_f32_16x16x4_f32 v[132:135], v100, v36, v[132:135]
	v_mfma_f32_16x16x4_f32 v[136:139], v100, v52, v[136:139]
	v_mfma_f32_16x16x4_f32 v[140:143], v100, v68, v[140:143]
	v_mfma_f32_16x16x4_f32 v[128:131], v101, v21, v[128:131]
	v_mfma_f32_16x16x4_f32 v[132:135], v101, v37, v[132:135]
	v_mfma_f32_16x16x4_f32 v[136:139], v101, v53, v[136:139]
	v_mfma_f32_16x16x4_f32 v[140:143], v101, v69, v[140:143]
	v_mfma_f32_16x16x4_f32 v[128:131], v102, v22, v[128:131]
	v_mfma_f32_16x16x4_f32 v[132:135], v102, v38, v[132:135]
	v_mfma_f32_16x16x4_f32 v[136:139], v102, v54, v[136:139]
	v_mfma_f32_16x16x4_f32 v[140:143], v102, v70, v[140:143]
	v_mfma_f32_16x16x4_f32 v[128:131], v103, v23, v[128:131]
	v_mfma_f32_16x16x4_f32 v[132:135], v103, v39, v[132:135]
	v_mfma_f32_16x16x4_f32 v[136:139], v103, v55, v[136:139]
	v_mfma_f32_16x16x4_f32 v[140:143], v103, v71, v[140:143]
	v_mfma_f32_16x16x4_f32 v[128:131], v104, v24, v[128:131]
	v_mfma_f32_16x16x4_f32 v[132:135], v104, v40, v[132:135]
	v_mfma_f32_16x16x4_f32 v[136:139], v104, v56, v[136:139]
	v_mfma_f32_16x16x4_f32 v[140:143], v104, v72, v[140:143]
	v_mfma_f32_16x16x4_f32 v[128:131], v105, v25, v[128:131]
	v_mfma_f32_16x16x4_f32 v[132:135], v105, v41, v[132:135]
	v_mfma_f32_16x16x4_f32 v[136:139], v105, v57, v[136:139]
	v_mfma_f32_16x16x4_f32 v[140:143], v105, v73, v[140:143]
	v_mfma_f32_16x16x4_f32 v[128:131], v106, v26, v[128:131]
	v_mfma_f32_16x16x4_f32 v[132:135], v106, v42, v[132:135]
	v_mfma_f32_16x16x4_f32 v[136:139], v106, v58, v[136:139]
	v_mfma_f32_16x16x4_f32 v[140:143], v106, v74, v[140:143]
	v_mfma_f32_16x16x4_f32 v[128:131], v107, v27, v[128:131]
	v_mfma_f32_16x16x4_f32 v[132:135], v107, v43, v[132:135]
	v_mfma_f32_16x16x4_f32 v[136:139], v107, v59, v[136:139]
	v_mfma_f32_16x16x4_f32 v[140:143], v107, v75, v[140:143]
	v_mfma_f32_16x16x4_f32 v[128:131], v108, v28, v[128:131]
	v_mfma_f32_16x16x4_f32 v[132:135], v108, v44, v[132:135]
	v_mfma_f32_16x16x4_f32 v[136:139], v108, v60, v[136:139]
	v_mfma_f32_16x16x4_f32 v[140:143], v108, v76, v[140:143]
	v_mfma_f32_16x16x4_f32 v[128:131], v109, v29, v[128:131]
	v_mfma_f32_16x16x4_f32 v[132:135], v109, v45, v[132:135]
	v_mfma_f32_16x16x4_f32 v[136:139], v109, v61, v[136:139]
	v_mfma_f32_16x16x4_f32 v[140:143], v109, v77, v[140:143]
	v_mfma_f32_16x16x4_f32 v[128:131], v110, v30, v[128:131]
	v_mfma_f32_16x16x4_f32 v[132:135], v110, v46, v[132:135]
	v_mfma_f32_16x16x4_f32 v[136:139], v110, v62, v[136:139]
	v_mfma_f32_16x16x4_f32 v[140:143], v110, v78, v[140:143]
	v_mfma_f32_16x16x4_f32 v[128:131], v111, v31, v[128:131]
	v_mfma_f32_16x16x4_f32 v[132:135], v111, v47, v[132:135]
	v_mfma_f32_16x16x4_f32 v[136:139], v111, v63, v[136:139]
	v_mfma_f32_16x16x4_f32 v[140:143], v111, v79, v[140:143]
	s_nop 9
	global_store_dword v[144:145], v128, off
	global_store_dword v[144:145], v132, off offset:64
	global_store_dword v[144:145], v136, off offset:128
	global_store_dword v[144:145], v140, off offset:192
	global_store_dword v[144:145], v129, off offset:3072
	global_store_dword v[144:145], v133, off offset:3136
	global_store_dword v[144:145], v137, off offset:3200
	global_store_dword v[144:145], v141, off offset:3264
	global_store_dword v[146:147], v130, off
	global_store_dword v[146:147], v134, off offset:64
	global_store_dword v[146:147], v138, off offset:128
	global_store_dword v[146:147], v142, off offset:192
	global_store_dword v[146:147], v131, off offset:3072
	global_store_dword v[146:147], v135, off offset:3136
	global_store_dword v[146:147], v139, off offset:3200
	global_store_dword v[146:147], v143, off offset:3264
	v_mov_b32_e32 v144, v4
	v_mov_b32_e32 v145, v5
	v_mov_b32_e32 v146, v6
	v_mov_b32_e32 v147, v7
	v_lshl_add_u64 v[156:157], v[156:157], 0, s[4:5]
	v_lshl_add_u64 v[4:5], v[4:5], 0, s[4:5]
	v_lshl_add_u64 v[6:7], v[6:7], 0, s[4:5]
	global_load_dwordx4 v[96:99], v[156:157], off offset:0
	global_load_dwordx4 v[100:103], v[156:157], off offset:16
	global_load_dwordx4 v[104:107], v[156:157], off offset:32
	global_load_dwordx4 v[108:111], v[156:157], off offset:48
	global_load_dword v128, v[4:5], off
	global_load_dword v132, v[4:5], off offset:64
	global_load_dword v136, v[4:5], off offset:128
	global_load_dword v140, v[4:5], off offset:192
	global_load_dword v129, v[4:5], off offset:3072
	global_load_dword v133, v[4:5], off offset:3136
	global_load_dword v137, v[4:5], off offset:3200
	global_load_dword v141, v[4:5], off offset:3264
	global_load_dword v130, v[6:7], off
	global_load_dword v134, v[6:7], off offset:64
	global_load_dword v138, v[6:7], off offset:128
	global_load_dword v142, v[6:7], off offset:192
	global_load_dword v131, v[6:7], off offset:3072
	global_load_dword v135, v[6:7], off offset:3136
	global_load_dword v139, v[6:7], off offset:3200
	global_load_dword v143, v[6:7], off offset:3264
	s_waitcnt vmcnt(36)
; __device__ __forceinline__ void phase_scan3(const Params& p, const Lt& lt, unsigned char* lds) {
;     ...
;         for (int tt = 0; tt < 4; ++tt) {
;             float av[16];
; #pragma unroll
;             for (int ks = 0; ks < 16; ++ks) av[ks] = zb[(size_t)tt * 16 * RW + 4 * ks];
;             f32x4 acc[4];
; #pragma unroll
;             for (int ti = 0; ti < 4; ++ti)
; #pragma unroll
;                 for (int r = 0; r < 4; ++r) acc[ti][r] = yb[(size_t)(tt * 16 + r) * RW + ti * 16];
; #pragma unroll
;             for (int ks = 0; ks < 16; ++ks)
; #pragma unroll
;                 for (int ti = 0; ti < 4; ++ti) acc[ti] = __builtin_amdgcn_mfma_f32_16x16x4f32(av[ks], bv[ti][ks], acc[ti], 0, 0, 0);
; #pragma unroll
;             for (int ti = 0; ti < 4; ++ti)
; #pragma unroll
;                 for (int r = 0; r < 4; ++r) yb[(size_t)(tt * 16 + r) * RW + ti * 16] = acc[ti][r];
;         }
	v_mfma_f32_16x16x4_f32 v[112:115], v80, v16, v[112:115]
	v_mfma_f32_16x16x4_f32 v[116:119], v80, v32, v[116:119]
	v_mfma_f32_16x16x4_f32 v[120:123], v80, v48, v[120:123]
	v_mfma_f32_16x16x4_f32 v[124:127], v80, v64, v[124:127]
	v_mfma_f32_16x16x4_f32 v[112:115], v81, v17, v[112:115]
	v_mfma_f32_16x16x4_f32 v[116:119], v81, v33, v[116:119]
	v_mfma_f32_16x16x4_f32 v[120:123], v81, v49, v[120:123]
	v_mfma_f32_16x16x4_f32 v[124:127], v81, v65, v[124:127]
	v_mfma_f32_16x16x4_f32 v[112:115], v82, v18, v[112:115]
	v_mfma_f32_16x16x4_f32 v[116:119], v82, v34, v[116:119]
	v_mfma_f32_16x16x4_f32 v[120:123], v82, v50, v[120:123]
	v_mfma_f32_16x16x4_f32 v[124:127], v82, v66, v[124:127]
	v_mfma_f32_16x16x4_f32 v[112:115], v83, v19, v[112:115]
	v_mfma_f32_16x16x4_f32 v[116:119], v83, v35, v[116:119]
	v_mfma_f32_16x16x4_f32 v[120:123], v83, v51, v[120:123]
	v_mfma_f32_16x16x4_f32 v[124:127], v83, v67, v[124:127]
	v_mfma_f32_16x16x4_f32 v[112:115], v84, v20, v[112:115]
	v_mfma_f32_16x16x4_f32 v[116:119], v84, v36, v[116:119]
	v_mfma_f32_16x16x4_f32 v[120:123], v84, v52, v[120:123]
	v_mfma_f32_16x16x4_f32 v[124:127], v84, v68, v[124:127]
	v_mfma_f32_16x16x4_f32 v[112:115], v85, v21, v[112:115]
	v_mfma_f32_16x16x4_f32 v[116:119], v85, v37, v[116:119]
	v_mfma_f32_16x16x4_f32 v[120:123], v85, v53, v[120:123]
	v_mfma_f32_16x16x4_f32 v[124:127], v85, v69, v[124:127]
	v_mfma_f32_16x16x4_f32 v[112:115], v86, v22, v[112:115]
	v_mfma_f32_16x16x4_f32 v[116:119], v86, v38, v[116:119]
	v_mfma_f32_16x16x4_f32 v[120:123], v86, v54, v[120:123]
	v_mfma_f32_16x16x4_f32 v[124:127], v86, v70, v[124:127]
	v_mfma_f32_16x16x4_f32 v[112:115], v87, v23, v[112:115]
	v_mfma_f32_16x16x4_f32 v[116:119], v87, v39, v[116:119]
	v_mfma_f32_16x16x4_f32 v[120:123], v87, v55, v[120:123]
	v_mfma_f32_16x16x4_f32 v[124:127], v87, v71, v[124:127]
	v_mfma_f32_16x16x4_f32 v[112:115], v88, v24, v[112:115]
	v_mfma_f32_16x16x4_f32 v[116:119], v88, v40, v[116:119]
	v_mfma_f32_16x16x4_f32 v[120:123], v88, v56, v[120:123]
	v_mfma_f32_16x16x4_f32 v[124:127], v88, v72, v[124:127]
	v_mfma_f32_16x16x4_f32 v[112:115], v89, v25, v[112:115]
	v_mfma_f32_16x16x4_f32 v[116:119], v89, v41, v[116:119]
	v_mfma_f32_16x16x4_f32 v[120:123], v89, v57, v[120:123]
	v_mfma_f32_16x16x4_f32 v[124:127], v89, v73, v[124:127]
	v_mfma_f32_16x16x4_f32 v[112:115], v90, v26, v[112:115]
	v_mfma_f32_16x16x4_f32 v[116:119], v90, v42, v[116:119]
	v_mfma_f32_16x16x4_f32 v[120:123], v90, v58, v[120:123]
	v_mfma_f32_16x16x4_f32 v[124:127], v90, v74, v[124:127]
	v_mfma_f32_16x16x4_f32 v[112:115], v91, v27, v[112:115]
	v_mfma_f32_16x16x4_f32 v[116:119], v91, v43, v[116:119]
	v_mfma_f32_16x16x4_f32 v[120:123], v91, v59, v[120:123]
	v_mfma_f32_16x16x4_f32 v[124:127], v91, v75, v[124:127]
	v_mfma_f32_16x16x4_f32 v[112:115], v92, v28, v[112:115]
	v_mfma_f32_16x16x4_f32 v[116:119], v92, v44, v[116:119]
	v_mfma_f32_16x16x4_f32 v[120:123], v92, v60, v[120:123]
	v_mfma_f32_16x16x4_f32 v[124:127], v92, v76, v[124:127]
	v_mfma_f32_16x16x4_f32 v[112:115], v93, v29, v[112:115]
	v_mfma_f32_16x16x4_f32 v[116:119], v93, v45, v[116:119]
	v_mfma_f32_16x16x4_f32 v[120:123], v93, v61, v[120:123]
	v_mfma_f32_16x16x4_f32 v[124:127], v93, v77, v[124:127]
	v_mfma_f32_16x16x4_f32 v[112:115], v94, v30, v[112:115]
	v_mfma_f32_16x16x4_f32 v[116:119], v94, v46, v[116:119]
	v_mfma_f32_16x16x4_f32 v[120:123], v94, v62, v[120:123]
	v_mfma_f32_16x16x4_f32 v[124:127], v94, v78, v[124:127]
	v_mfma_f32_16x16x4_f32 v[112:115], v95, v31, v[112:115]
	v_mfma_f32_16x16x4_f32 v[116:119], v95, v47, v[116:119]
	v_mfma_f32_16x16x4_f32 v[120:123], v95, v63, v[120:123]
	v_mfma_f32_16x16x4_f32 v[124:127], v95, v79, v[124:127]
	s_nop 9
	global_store_dword v[144:145], v112, off
	global_store_dword v[144:145], v116, off offset:64
	global_store_dword v[144:145], v120, off offset:128
	global_store_dword v[144:145], v124, off offset:192
	global_store_dword v[144:145], v113, off offset:3072
	global_store_dword v[144:145], v117, off offset:3136
	global_store_dword v[144:145], v121, off offset:3200
	global_store_dword v[144:145], v125, off offset:3264
	global_store_dword v[146:147], v114, off
	global_store_dword v[146:147], v118, off offset:64
	global_store_dword v[146:147], v122, off offset:128
	global_store_dword v[146:147], v126, off offset:192
	global_store_dword v[146:147], v115, off offset:3072
	global_store_dword v[146:147], v119, off offset:3136
	global_store_dword v[146:147], v123, off offset:3200
	global_store_dword v[146:147], v127, off offset:3264
	s_waitcnt vmcnt(16)
; __device__ __forceinline__ void phase_scan3(const Params& p, const Lt& lt, unsigned char* lds) {
;     ...
;         for (int tt = 0; tt < 4; ++tt) {
;             float av[16];
; #pragma unroll
;             for (int ks = 0; ks < 16; ++ks) av[ks] = zb[(size_t)tt * 16 * RW + 4 * ks];
;             f32x4 acc[4];
; #pragma unroll
;             for (int ti = 0; ti < 4; ++ti)
; #pragma unroll
;                 for (int r = 0; r < 4; ++r) acc[ti][r] = yb[(size_t)(tt * 16 + r) * RW + ti * 16];
; #pragma unroll
;             for (int ks = 0; ks < 16; ++ks)
; #pragma unroll
;                 for (int ti = 0; ti < 4; ++ti) acc[ti] = __builtin_amdgcn_mfma_f32_16x16x4f32(av[ks], bv[ti][ks], acc[ti], 0, 0, 0);
; #pragma unroll
;             for (int ti = 0; ti < 4; ++ti)
; #pragma unroll
;                 for (int r = 0; r < 4; ++r) yb[(size_t)(tt * 16 + r) * RW + ti * 16] = acc[ti][r];
;         }
	v_mfma_f32_16x16x4_f32 v[128:131], v96, v16, v[128:131]
	v_mfma_f32_16x16x4_f32 v[132:135], v96, v32, v[132:135]
	v_mfma_f32_16x16x4_f32 v[136:139], v96, v48, v[136:139]
	v_mfma_f32_16x16x4_f32 v[140:143], v96, v64, v[140:143]
	v_mfma_f32_16x16x4_f32 v[128:131], v97, v17, v[128:131]
	v_mfma_f32_16x16x4_f32 v[132:135], v97, v33, v[132:135]
	v_mfma_f32_16x16x4_f32 v[136:139], v97, v49, v[136:139]
	v_mfma_f32_16x16x4_f32 v[140:143], v97, v65, v[140:143]
	v_mfma_f32_16x16x4_f32 v[128:131], v98, v18, v[128:131]
	v_mfma_f32_16x16x4_f32 v[132:135], v98, v34, v[132:135]
	v_mfma_f32_16x16x4_f32 v[136:139], v98, v50, v[136:139]
	v_mfma_f32_16x16x4_f32 v[140:143], v98, v66, v[140:143]
	v_mfma_f32_16x16x4_f32 v[128:131], v99, v19, v[128:131]
	v_mfma_f32_16x16x4_f32 v[132:135], v99, v35, v[132:135]
	v_mfma_f32_16x16x4_f32 v[136:139], v99, v51, v[136:139]
	v_mfma_f32_16x16x4_f32 v[140:143], v99, v67, v[140:143]
	v_mfma_f32_16x16x4_f32 v[128:131], v100, v20, v[128:131]
	v_mfma_f32_16x16x4_f32 v[132:135], v100, v36, v[132:135]
	v_mfma_f32_16x16x4_f32 v[136:139], v100, v52, v[136:139]
	v_mfma_f32_16x16x4_f32 v[140:143], v100, v68, v[140:143]
	v_mfma_f32_16x16x4_f32 v[128:131], v101, v21, v[128:131]
	v_mfma_f32_16x16x4_f32 v[132:135], v101, v37, v[132:135]
	v_mfma_f32_16x16x4_f32 v[136:139], v101, v53, v[136:139]
	v_mfma_f32_16x16x4_f32 v[140:143], v101, v69, v[140:143]
	v_mfma_f32_16x16x4_f32 v[128:131], v102, v22, v[128:131]
	v_mfma_f32_16x16x4_f32 v[132:135], v102, v38, v[132:135]
	v_mfma_f32_16x16x4_f32 v[136:139], v102, v54, v[136:139]
	v_mfma_f32_16x16x4_f32 v[140:143], v102, v70, v[140:143]
	v_mfma_f32_16x16x4_f32 v[128:131], v103, v23, v[128:131]
	v_mfma_f32_16x16x4_f32 v[132:135], v103, v39, v[132:135]
	v_mfma_f32_16x16x4_f32 v[136:139], v103, v55, v[136:139]
	v_mfma_f32_16x16x4_f32 v[140:143], v103, v71, v[140:143]
	v_mfma_f32_16x16x4_f32 v[128:131], v104, v24, v[128:131]
	v_mfma_f32_16x16x4_f32 v[132:135], v104, v40, v[132:135]
	v_mfma_f32_16x16x4_f32 v[136:139], v104, v56, v[136:139]
	v_mfma_f32_16x16x4_f32 v[140:143], v104, v72, v[140:143]
	v_mfma_f32_16x16x4_f32 v[128:131], v105, v25, v[128:131]
	v_mfma_f32_16x16x4_f32 v[132:135], v105, v41, v[132:135]
	v_mfma_f32_16x16x4_f32 v[136:139], v105, v57, v[136:139]
	v_mfma_f32_16x16x4_f32 v[140:143], v105, v73, v[140:143]
	v_mfma_f32_16x16x4_f32 v[128:131], v106, v26, v[128:131]
	v_mfma_f32_16x16x4_f32 v[132:135], v106, v42, v[132:135]
	v_mfma_f32_16x16x4_f32 v[136:139], v106, v58, v[136:139]
	v_mfma_f32_16x16x4_f32 v[140:143], v106, v74, v[140:143]
	v_mfma_f32_16x16x4_f32 v[128:131], v107, v27, v[128:131]
	v_mfma_f32_16x16x4_f32 v[132:135], v107, v43, v[132:135]
	v_mfma_f32_16x16x4_f32 v[136:139], v107, v59, v[136:139]
	v_mfma_f32_16x16x4_f32 v[140:143], v107, v75, v[140:143]
	v_mfma_f32_16x16x4_f32 v[128:131], v108, v28, v[128:131]
	v_mfma_f32_16x16x4_f32 v[132:135], v108, v44, v[132:135]
	v_mfma_f32_16x16x4_f32 v[136:139], v108, v60, v[136:139]
	v_mfma_f32_16x16x4_f32 v[140:143], v108, v76, v[140:143]
	v_mfma_f32_16x16x4_f32 v[128:131], v109, v29, v[128:131]
	v_mfma_f32_16x16x4_f32 v[132:135], v109, v45, v[132:135]
	v_mfma_f32_16x16x4_f32 v[136:139], v109, v61, v[136:139]
	v_mfma_f32_16x16x4_f32 v[140:143], v109, v77, v[140:143]
	v_mfma_f32_16x16x4_f32 v[128:131], v110, v30, v[128:131]
	v_mfma_f32_16x16x4_f32 v[132:135], v110, v46, v[132:135]
	v_mfma_f32_16x16x4_f32 v[136:139], v110, v62, v[136:139]
	v_mfma_f32_16x16x4_f32 v[140:143], v110, v78, v[140:143]
	v_mfma_f32_16x16x4_f32 v[128:131], v111, v31, v[128:131]
	v_mfma_f32_16x16x4_f32 v[132:135], v111, v47, v[132:135]
	v_mfma_f32_16x16x4_f32 v[136:139], v111, v63, v[136:139]
	v_mfma_f32_16x16x4_f32 v[140:143], v111, v79, v[140:143]
	s_nop 9
	global_store_dword v[4:5], v128, off
	global_store_dword v[4:5], v132, off offset:64
	global_store_dword v[4:5], v136, off offset:128
	global_store_dword v[4:5], v140, off offset:192
	global_store_dword v[4:5], v129, off offset:3072
	global_store_dword v[4:5], v133, off offset:3136
	global_store_dword v[4:5], v137, off offset:3200
	global_store_dword v[4:5], v141, off offset:3264
	global_store_dword v[6:7], v130, off
	global_store_dword v[6:7], v134, off offset:64
	global_store_dword v[6:7], v138, off offset:128
	global_store_dword v[6:7], v142, off offset:192
	global_store_dword v[6:7], v131, off offset:3072
	global_store_dword v[6:7], v135, off offset:3136
	global_store_dword v[6:7], v139, off offset:3200
	global_store_dword v[6:7], v143, off offset:3264
	s_add_i32 s0, s0, s84
	s_cmpk_gt_i32 s0, 0x5ff
	s_cbranch_scc0 .LBB0_137

; __device__ __forceinline__ void phase_scan2(const Params& p, const Lt& lt, int nblk, unsigned char* lds) {
;     ...
;             if (w < 4) {
; #pragma unroll
;                 for (int r = 0; r < 4; ++r) So[(size_t)g * 4096 + r * 64] = s4[r];
;                 const float* As = Sx + (g & 1) * 16 * SP + fi * SP + fq;
;                 const float* Bs = Rg + slot * SLOTF + fq * 64 + 16 * w + fi;
;                 const float* Lr = Rg + slot * SLOTF + 4096 + (4 * fq) * 64 + 16 * w + fi;
;                 float av[16], bv[16];
; #pragma unroll
;                 for (int ks = 0; ks < 16; ++ks) { av[ks] = As[4 * ks]; bv[ks] = Bs[(4 * ks) * 64]; }
;                 f32x4 c0 = {Lr[0], Lr[64], Lr[128], Lr[192]}, c1 = {0.f, 0.f, 0.f, 0.f};
;                 asm volatile("s_waitcnt lgkmcnt(0)" ::: "memory");
; #pragma unroll
;                 for (int ks = 0; ks < 16; ks += 2) {
;                     c0 = __builtin_amdgcn_mfma_f32_16x16x4f32(av[ks], bv[ks], c0, 0, 0, 0);
;                     c1 = __builtin_amdgcn_mfma_f32_16x16x4f32(av[ks + 1], bv[ks + 1], c1, 0, 0, 0);
;                 }
;                 s4 = c0 + c1;
;                 float* Sn = Sx + ((g + 1) & 1) * 16 * SP + (4 * fq) * SP + 16 * w + fi;
; #pragma unroll
;                 for (int r = 0; r < 4; ++r) Sn[r * SP] = s4[r];
;             }
.LBB0_167:
	s_mul_i32 s28, s31, 0x5000
	s_min_u32 s10, s51, 0x79
	s_add_i32 s29, s28, 0xffffb000
	s_cmp_lg_u32 s31, 0
	s_cselect_b32 s29, s29, 0x19000
	s_lshl_b32 s10, s10, 12
	s_addk_i32 s10, 0x5000
	s_add_i32 s29, s29, 0
	s_lshl_b32 s10, s10, 2
	s_add_i32 s52, s29, s37
	s_waitcnt lgkmcnt(0)
	s_barrier
	v_lshl_add_u64 v[24:25], v[8:9], 0, s[10:11]
	s_mov_b32 m0, s52
	s_mov_b64 s[54:55], 0x400
	global_load_lds_dwordx4 v[24:25], off
	v_lshl_add_u64 v[24:25], v[24:25], 0, s[54:55]
	s_add_i32 m0, s52, 0x400
	s_and_b64 vcc, exec, s[4:5]
	global_load_lds_dwordx4 v[24:25], off
	s_cbranch_vccnz .LBB0_162
	v_lshl_add_u64 v[24:25], v[10:11], 0, s[10:11]
	s_add_i32 s10, s29, s38
	s_add_i32 m0, s10, 0x4000
	s_and_b32 s10, s30, 16
	global_load_lds_dwordx4 v[24:25], off
	s_add_i32 s28, s28, 0
	s_mul_i32 s29, s10, 0x108
	s_add_i32 s28, s49, s28
	v_add_u32_e32 v5, s29, v19
	v_add3_u32 v26, s28, v20, v4
	v_add3_u32 v36, s28, v18, v4
	ds_read2st64_b32 v[24:25], v26 offset0:64 offset1:65
	ds_read2st64_b32 v[26:27], v26 offset0:66 offset1:67
	ds_read2_b32 v[40:41], v5 offset1:4
	ds_read2st64_b32 v[56:57], v36 offset1:4
	ds_read2_b32 v[42:43], v5 offset0:8 offset1:12
	ds_read2st64_b32 v[58:59], v36 offset0:8 offset1:12
	ds_read2_b32 v[44:45], v5 offset0:16 offset1:20
	ds_read2st64_b32 v[60:61], v36 offset0:16 offset1:20
	ds_read2_b32 v[46:47], v5 offset0:24 offset1:28
	ds_read2st64_b32 v[62:63], v36 offset0:24 offset1:28
	ds_read2_b32 v[48:49], v5 offset0:32 offset1:36
	ds_read2st64_b32 v[64:65], v36 offset0:32 offset1:36
	ds_read2_b32 v[50:51], v5 offset0:40 offset1:44
	ds_read2st64_b32 v[66:67], v36 offset0:40 offset1:44
	ds_read2_b32 v[52:53], v5 offset0:48 offset1:52
	ds_read2st64_b32 v[68:69], v36 offset0:48 offset1:52
	ds_read2_b32 v[54:55], v5 offset0:56 offset1:60
	ds_read2st64_b32 v[70:71], v36 offset0:56 offset1:60
	s_xor_b32 s10, s10, 16
	s_mulk_i32 s10, 0x108
	global_store_dword v[12:13], v16, off offset:-512
	global_store_dword v[12:13], v17, off offset:-256
	global_store_dword v[12:13], v14, off
	global_store_dword v[12:13], v15, off offset:256
	v_add_u32_e32 v5, s10, v21
	s_waitcnt lgkmcnt(14)
	v_mfma_f32_16x16x4_f32 v[24:27], v40, v56, v[24:27]
	v_mfma_f32_16x16x4_f32 v[28:31], v41, v57, 0
	s_waitcnt lgkmcnt(12)
	v_mfma_f32_16x16x4_f32 v[24:27], v42, v58, v[24:27]
	v_mfma_f32_16x16x4_f32 v[28:31], v43, v59, v[28:31]
	s_waitcnt lgkmcnt(10)
	v_mfma_f32_16x16x4_f32 v[24:27], v44, v60, v[24:27]
	v_mfma_f32_16x16x4_f32 v[28:31], v45, v61, v[28:31]
	s_waitcnt lgkmcnt(8)
	v_mfma_f32_16x16x4_f32 v[24:27], v46, v62, v[24:27]
	v_mfma_f32_16x16x4_f32 v[28:31], v47, v63, v[28:31]
	s_waitcnt lgkmcnt(6)
	v_mfma_f32_16x16x4_f32 v[24:27], v48, v64, v[24:27]
	v_mfma_f32_16x16x4_f32 v[28:31], v49, v65, v[28:31]
	s_waitcnt lgkmcnt(4)
	v_mfma_f32_16x16x4_f32 v[24:27], v50, v66, v[24:27]
	v_mfma_f32_16x16x4_f32 v[28:31], v51, v67, v[28:31]
	s_waitcnt lgkmcnt(2)
	v_mfma_f32_16x16x4_f32 v[24:27], v52, v68, v[24:27]
	v_mfma_f32_16x16x4_f32 v[28:31], v53, v69, v[28:31]
	s_waitcnt lgkmcnt(0)
	v_mfma_f32_16x16x4_f32 v[24:27], v54, v70, v[24:27]
	v_mfma_f32_16x16x4_f32 v[28:31], v55, v71, v[28:31]
	s_nop 9
	v_pk_add_f32 v[14:15], v[26:27], v[30:31]
	v_pk_add_f32 v[16:17], v[24:25], v[28:29]
	ds_write2_b32 v5, v16, v17 offset1:66
	ds_write2_b32 v5, v14, v15 offset0:132 offset1:198
	s_branch .LBB0_162
